# grid barrier: non-leader workgroups poll the cross-XCD release word directly instead of waiting for their XCD leader's relay (one hop less); on top of v43
# baseline (speedup 1.0000x reference)
; __device__ __forceinline__ unsigned xb_ld(unsigned* p)              { return __hip_atomic_load(p, __ATOMIC_RELAXED, __HIP_MEMORY_SCOPE_AGENT); }
; __device__ __forceinline__ unsigned xb_add(unsigned* p, unsigned v) { return __hip_atomic_fetch_add(p, v, __ATOMIC_RELAXED, __HIP_MEMORY_SCOPE_AGENT); }
; #define XB_SPIN(cond, bar) do { unsigned _sp = 0; while (cond) { __builtin_amdgcn_s_sleep(1); \
;     if ((++_sp & 255u) == 0u) { if (xb_ld(&(bar)[XB_TMO])) break; if (_sp > XB_SPIN_CAP) { atomicAdd(&(bar)[XB_TMO], 1u); break; } } } } while (0)
; __device__ __forceinline__ void xcd_barrier(const XcdBarrier& b) {
;     ...
;         unsigned nloc = b.st[0], nx = b.st[1];
;         if (nloc == 0u) { xcd_barrier_complete(bar, b.x, nloc, nx); b.st[0] = nloc; b.st[1] = nx; }
;         const unsigned old = xb_add(&bar[XB_XSUB(b.x)], 1u);
;         const unsigned gen = old / nloc;
;         if (old + 1u == (gen + 1u) * nloc) {
;             __builtin_amdgcn_fence(__ATOMIC_RELEASE, "agent");
;             asm volatile("s_waitcnt vmcnt(0)" ::: "memory");
;             const unsigned og = xb_add(&bar[XB_TOP], 1u);
;             const unsigned tg = og / nx;
;             if (og + 1u == (tg + 1u) * nx) xb_add(&bar[XB_TOPGEN], 1u);
;             else XB_SPIN(xb_ld(&bar[XB_TOPGEN]) == tg, bar);
;             __builtin_amdgcn_fence(__ATOMIC_ACQUIRE, "agent");
;             xb_add(&bar[XB_XGEN(b.x)], 1u);
;             asm volatile("s_waitcnt vmcnt(0)" ::: "memory");
;         } else {
;             XB_SPIN(xb_ld(&bar[XB_XGEN(b.x)]) == gen, bar);
;             __builtin_amdgcn_fence(__ATOMIC_ACQUIRE, "agent");
;             asm volatile("s_waitcnt vmcnt(0)" ::: "memory");
.LBB0_393:
	s_or_b64 exec, exec, s[40:41]
	v_cvt_f32_u32_e32 v5, v3
	s_waitcnt vmcnt(0)
	v_readfirstlane_b32 s30, v4
	v_sub_u32_e32 v4, 0, v3
	v_rcp_iflag_f32_e32 v5, v5
	v_add_u32_e32 v6, s30, v0
	v_mul_f32_e32 v5, 0x4f7ffffe, v5
	v_cvt_u32_f32_e32 v5, v5
	v_mul_lo_u32 v0, v4, v5
	v_mul_hi_u32 v0, v5, v0
	v_add_u32_e32 v0, v5, v0
	v_mul_hi_u32 v0, v6, v0
	v_mul_lo_u32 v4, v0, v3
	v_sub_u32_e32 v4, v6, v4
	v_add_u32_e32 v5, 1, v0
	v_cmp_ge_u32_e32 vcc, v4, v3
	s_nop 1
	v_cndmask_b32_e32 v0, v0, v5, vcc
	v_sub_u32_e32 v5, v4, v3
	v_cndmask_b32_e32 v4, v4, v5, vcc
	v_add_u32_e32 v5, 1, v0
	v_cmp_ge_u32_e32 vcc, v4, v3
	v_add_u32_e32 v4, 1, v6
	s_nop 0
	v_cndmask_b32_e32 v0, v0, v5, vcc
	v_mul_lo_u32 v5, v3, v0
	v_add_u32_e32 v3, v5, v3
	v_cmp_ne_u32_e32 vcc, v4, v3
	s_and_saveexec_b64 s[34:35], vcc
	s_xor_b64 s[40:41], exec, s[34:35]
	s_cbranch_execz .LBB0_407
	v_readlane_b32 s30, v254, 2
	v_readlane_b32 s31, v254, 3
	s_waitcnt lgkmcnt(0)
	s_nop 3
	global_load_dword v2, v1, s[30:31] sc1
	s_waitcnt vmcnt(0)
	v_cmp_eq_u32_e32 vcc, v2, v0
	s_and_saveexec_b64 s[42:43], vcc
	s_cbranch_execz .LBB0_406
	s_mov_b32 s34, 1
	s_mov_b64 s[44:45], 0
	s_branch .LBB0_397

; __device__ __forceinline__ unsigned xb_ld(unsigned* p)              { return __hip_atomic_load(p, __ATOMIC_RELAXED, __HIP_MEMORY_SCOPE_AGENT); }
; __device__ __forceinline__ unsigned xb_add(unsigned* p, unsigned v) { return __hip_atomic_fetch_add(p, v, __ATOMIC_RELAXED, __HIP_MEMORY_SCOPE_AGENT); }
; #define XB_SPIN(cond, bar) do { unsigned _sp = 0; while (cond) { __builtin_amdgcn_s_sleep(1); \
;     if ((++_sp & 255u) == 0u) { if (xb_ld(&(bar)[XB_TMO])) break; if (_sp > XB_SPIN_CAP) { atomicAdd(&(bar)[XB_TMO], 1u); break; } } } } while (0)
; __device__ __forceinline__ void xcd_barrier(const XcdBarrier& b) {
;     ...
;         unsigned nloc = b.st[0], nx = b.st[1];
;         if (nloc == 0u) { xcd_barrier_complete(bar, b.x, nloc, nx); b.st[0] = nloc; b.st[1] = nx; }
;         const unsigned old = xb_add(&bar[XB_XSUB(b.x)], 1u);
;         const unsigned gen = old / nloc;
;         if (old + 1u == (gen + 1u) * nloc) {
;             __builtin_amdgcn_fence(__ATOMIC_RELEASE, "agent");
;             asm volatile("s_waitcnt vmcnt(0)" ::: "memory");
;             const unsigned og = xb_add(&bar[XB_TOP], 1u);
;             const unsigned tg = og / nx;
;             if (og + 1u == (tg + 1u) * nx) xb_add(&bar[XB_TOPGEN], 1u);
;             else XB_SPIN(xb_ld(&bar[XB_TOPGEN]) == tg, bar);
;             __builtin_amdgcn_fence(__ATOMIC_ACQUIRE, "agent");
;             xb_add(&bar[XB_XGEN(b.x)], 1u);
;             asm volatile("s_waitcnt vmcnt(0)" ::: "memory");
;         } else {
;             XB_SPIN(xb_ld(&bar[XB_XGEN(b.x)]) == gen, bar);
;             __builtin_amdgcn_fence(__ATOMIC_ACQUIRE, "agent");
;             asm volatile("s_waitcnt vmcnt(0)" ::: "memory");
.LBB0_472:
	s_or_b64 exec, exec, s[20:21]
	v_cvt_f32_u32_e32 v5, v3
	s_waitcnt vmcnt(0)
	v_readfirstlane_b32 s6, v4
	v_sub_u32_e32 v4, 0, v3
	v_rcp_iflag_f32_e32 v5, v5
	v_add_u32_e32 v6, s6, v0
	v_mul_f32_e32 v5, 0x4f7ffffe, v5
	v_cvt_u32_f32_e32 v5, v5
	v_mul_lo_u32 v0, v4, v5
	v_mul_hi_u32 v0, v5, v0
	v_add_u32_e32 v0, v5, v0
	v_mul_hi_u32 v0, v6, v0
	v_mul_lo_u32 v4, v0, v3
	v_sub_u32_e32 v4, v6, v4
	v_add_u32_e32 v5, 1, v0
	v_cmp_ge_u32_e32 vcc, v4, v3
	s_nop 1
	v_cndmask_b32_e32 v0, v0, v5, vcc
	v_sub_u32_e32 v5, v4, v3
	v_cndmask_b32_e32 v4, v4, v5, vcc
	v_add_u32_e32 v5, 1, v0
	v_cmp_ge_u32_e32 vcc, v4, v3
	v_add_u32_e32 v4, 1, v6
	s_nop 0
	v_cndmask_b32_e32 v0, v0, v5, vcc
	v_mul_lo_u32 v5, v3, v0
	v_add_u32_e32 v3, v5, v3
	v_cmp_ne_u32_e32 vcc, v4, v3
	s_and_saveexec_b64 s[20:21], vcc
	s_xor_b64 s[20:21], exec, s[20:21]
	s_cbranch_execz .LBB0_486
	v_readlane_b32 s30, v254, 2
	v_readlane_b32 s31, v254, 3
	s_waitcnt lgkmcnt(0)
	s_nop 3
	global_load_dword v2, v1, s[30:31] sc1
	s_waitcnt vmcnt(0)
	v_cmp_eq_u32_e32 vcc, v2, v0
	s_and_saveexec_b64 s[40:41], vcc
	s_cbranch_execz .LBB0_485
	s_mov_b32 s6, 1
	s_mov_b64 s[42:43], 0
	s_branch .LBB0_476

; __device__ __forceinline__ unsigned xb_ld(unsigned* p)              { return __hip_atomic_load(p, __ATOMIC_RELAXED, __HIP_MEMORY_SCOPE_AGENT); }
; __device__ __forceinline__ unsigned xb_add(unsigned* p, unsigned v) { return __hip_atomic_fetch_add(p, v, __ATOMIC_RELAXED, __HIP_MEMORY_SCOPE_AGENT); }
; #define XB_SPIN(cond, bar) do { unsigned _sp = 0; while (cond) { __builtin_amdgcn_s_sleep(1); \
;     if ((++_sp & 255u) == 0u) { if (xb_ld(&(bar)[XB_TMO])) break; if (_sp > XB_SPIN_CAP) { atomicAdd(&(bar)[XB_TMO], 1u); break; } } } } while (0)
; __device__ __forceinline__ void xcd_barrier(const XcdBarrier& b) {
;     ...
;         unsigned nloc = b.st[0], nx = b.st[1];
;         if (nloc == 0u) { xcd_barrier_complete(bar, b.x, nloc, nx); b.st[0] = nloc; b.st[1] = nx; }
;         const unsigned old = xb_add(&bar[XB_XSUB(b.x)], 1u);
;         const unsigned gen = old / nloc;
;         if (old + 1u == (gen + 1u) * nloc) {
;             __builtin_amdgcn_fence(__ATOMIC_RELEASE, "agent");
;             asm volatile("s_waitcnt vmcnt(0)" ::: "memory");
;             const unsigned og = xb_add(&bar[XB_TOP], 1u);
;             const unsigned tg = og / nx;
;             if (og + 1u == (tg + 1u) * nx) xb_add(&bar[XB_TOPGEN], 1u);
;             else XB_SPIN(xb_ld(&bar[XB_TOPGEN]) == tg, bar);
;             __builtin_amdgcn_fence(__ATOMIC_ACQUIRE, "agent");
;             xb_add(&bar[XB_XGEN(b.x)], 1u);
;             asm volatile("s_waitcnt vmcnt(0)" ::: "memory");
;         } else {
;             XB_SPIN(xb_ld(&bar[XB_XGEN(b.x)]) == gen, bar);
;             __builtin_amdgcn_fence(__ATOMIC_ACQUIRE, "agent");
;             asm volatile("s_waitcnt vmcnt(0)" ::: "memory");
.LBB0_546:
	s_or_b64 exec, exec, s[20:21]
	v_cvt_f32_u32_e32 v5, v3
	s_waitcnt vmcnt(0)
	v_readfirstlane_b32 s20, v4
	v_sub_u32_e32 v4, 0, v3
	v_rcp_iflag_f32_e32 v5, v5
	v_add_u32_e32 v6, s20, v0
	v_mul_f32_e32 v5, 0x4f7ffffe, v5
	v_cvt_u32_f32_e32 v5, v5
	v_mul_lo_u32 v0, v4, v5
	v_mul_hi_u32 v0, v5, v0
	v_add_u32_e32 v0, v5, v0
	v_mul_hi_u32 v0, v6, v0
	v_mul_lo_u32 v4, v0, v3
	v_sub_u32_e32 v4, v6, v4
	v_add_u32_e32 v5, 1, v0
	v_cmp_ge_u32_e32 vcc, v4, v3
	s_nop 1
	v_cndmask_b32_e32 v0, v0, v5, vcc
	v_sub_u32_e32 v5, v4, v3
	v_cndmask_b32_e32 v4, v4, v5, vcc
	v_add_u32_e32 v5, 1, v0
	v_cmp_ge_u32_e32 vcc, v4, v3
	v_add_u32_e32 v4, 1, v6
	s_nop 0
	v_cndmask_b32_e32 v0, v0, v5, vcc
	v_mul_lo_u32 v5, v3, v0
	v_add_u32_e32 v3, v5, v3
	v_cmp_ne_u32_e32 vcc, v4, v3
	s_and_saveexec_b64 s[20:21], vcc
	s_xor_b64 s[20:21], exec, s[20:21]
	s_cbranch_execz .LBB0_560
	v_readlane_b32 s30, v254, 2
	v_readlane_b32 s31, v254, 3
	s_waitcnt lgkmcnt(0)
	s_nop 3
	global_load_dword v2, v1, s[30:31] sc1
	s_waitcnt vmcnt(0)
	v_cmp_eq_u32_e32 vcc, v2, v0
	s_and_saveexec_b64 s[40:41], vcc
	s_cbranch_execz .LBB0_559
	s_mov_b32 s33, 1
	s_mov_b64 s[42:43], 0
	s_branch .LBB0_550

; __device__ __forceinline__ unsigned xb_ld(unsigned* p)              { return __hip_atomic_load(p, __ATOMIC_RELAXED, __HIP_MEMORY_SCOPE_AGENT); }
; __device__ __forceinline__ unsigned xb_add(unsigned* p, unsigned v) { return __hip_atomic_fetch_add(p, v, __ATOMIC_RELAXED, __HIP_MEMORY_SCOPE_AGENT); }
; #define XB_SPIN(cond, bar) do { unsigned _sp = 0; while (cond) { __builtin_amdgcn_s_sleep(1); \
;     if ((++_sp & 255u) == 0u) { if (xb_ld(&(bar)[XB_TMO])) break; if (_sp > XB_SPIN_CAP) { atomicAdd(&(bar)[XB_TMO], 1u); break; } } } } while (0)
; __device__ __forceinline__ void xcd_barrier(const XcdBarrier& b) {
;     ...
;         unsigned nloc = b.st[0], nx = b.st[1];
;         if (nloc == 0u) { xcd_barrier_complete(bar, b.x, nloc, nx); b.st[0] = nloc; b.st[1] = nx; }
;         const unsigned old = xb_add(&bar[XB_XSUB(b.x)], 1u);
;         const unsigned gen = old / nloc;
;         if (old + 1u == (gen + 1u) * nloc) {
;             __builtin_amdgcn_fence(__ATOMIC_RELEASE, "agent");
;             asm volatile("s_waitcnt vmcnt(0)" ::: "memory");
;             const unsigned og = xb_add(&bar[XB_TOP], 1u);
;             const unsigned tg = og / nx;
;             if (og + 1u == (tg + 1u) * nx) xb_add(&bar[XB_TOPGEN], 1u);
;             else XB_SPIN(xb_ld(&bar[XB_TOPGEN]) == tg, bar);
;             __builtin_amdgcn_fence(__ATOMIC_ACQUIRE, "agent");
;             xb_add(&bar[XB_XGEN(b.x)], 1u);
;             asm volatile("s_waitcnt vmcnt(0)" ::: "memory");
;         } else {
;             XB_SPIN(xb_ld(&bar[XB_XGEN(b.x)]) == gen, bar);
;             __builtin_amdgcn_fence(__ATOMIC_ACQUIRE, "agent");
;             asm volatile("s_waitcnt vmcnt(0)" ::: "memory");
.LBB0_747:
	s_or_b64 exec, exec, s[20:21]
	v_cvt_f32_u32_e32 v5, v3
	s_waitcnt vmcnt(0)
	v_readfirstlane_b32 s20, v4
	v_sub_u32_e32 v4, 0, v3
	v_rcp_iflag_f32_e32 v5, v5
	v_add_u32_e32 v6, s20, v0
	v_mul_f32_e32 v5, 0x4f7ffffe, v5
	v_cvt_u32_f32_e32 v5, v5
	v_mul_lo_u32 v0, v4, v5
	v_mul_hi_u32 v0, v5, v0
	v_add_u32_e32 v0, v5, v0
	v_mul_hi_u32 v0, v6, v0
	v_mul_lo_u32 v4, v0, v3
	v_sub_u32_e32 v4, v6, v4
	v_add_u32_e32 v5, 1, v0
	v_cmp_ge_u32_e32 vcc, v4, v3
	s_nop 1
	v_cndmask_b32_e32 v0, v0, v5, vcc
	v_sub_u32_e32 v5, v4, v3
	v_cndmask_b32_e32 v4, v4, v5, vcc
	v_add_u32_e32 v5, 1, v0
	v_cmp_ge_u32_e32 vcc, v4, v3
	v_add_u32_e32 v4, 1, v6
	s_nop 0
	v_cndmask_b32_e32 v0, v0, v5, vcc
	v_mul_lo_u32 v5, v3, v0
	v_add_u32_e32 v3, v5, v3
	v_cmp_ne_u32_e32 vcc, v4, v3
	s_and_saveexec_b64 s[20:21], vcc
	s_xor_b64 s[20:21], exec, s[20:21]
	s_cbranch_execz .LBB0_761
	v_readlane_b32 s30, v254, 2
	v_readlane_b32 s31, v254, 3
	s_waitcnt lgkmcnt(0)
	s_nop 3
	global_load_dword v2, v1, s[30:31] sc1
	s_waitcnt vmcnt(0)
	v_cmp_eq_u32_e32 vcc, v2, v0
	s_and_saveexec_b64 s[42:43], vcc
	s_cbranch_execz .LBB0_760
	s_mov_b32 s33, 1
	s_mov_b64 s[44:45], 0
	s_branch .LBB0_751
